# v25 + peeled first K-loop pass (no accumulator clears, P1/P7) + relu quieting fusion + always-true P7 store guards dropped: fewer instructions on the unit-boundary critical path
# speedup vs baseline: 1.0019x; 1.0019x over previous
; __device__ __forceinline__ unsigned cvt_pk_bf16(float lo, float hi) { unsigned r; asm volatile("v_cvt_pk_bf16_f32 %0, %1, %2" : "=v"(r) : "v"(lo), "v"(hi)); return r; }
;     __device__ __forceinline__ void operator()(const f32x4 (&acc)[2][2][4][2], const Unit& u, int wr, int wc, int fr, int fq) const {
;         const int row0 = u.pm * BM + wr * 64 + fr, col0 = u.pn * BM + wc * CWS + 8 * fq;
;         float rs[2][4];
;         if (ROWSCALE) {
; #pragma unroll
;             for (int ai = 0; ai < 2; ++ai)
; #pragma unroll
;                 for (int m = 0; m < 4; ++m) { const f32x4 q = *(const f32x4*)(ssq4 + (size_t)(row0 + ai * HALF + m * 16) * 4); rs[ai][m] = 1.0f / sqrtf(((q[0] + q[1]) + (q[2] + q[3])) * (1.0f / 1024.0f) + eps); }
;         }
; #pragma unroll
;         for (int ai = 0; ai < 2; ++ai)
; #pragma unroll
;             for (int m = 0; m < 4; ++m) { bf16_t* rowp = O + (size_t)(row0 + ai * HALF + m * 16) * ldc + col0;
; #pragma unroll
;                 for (int bj = 0; bj < 2; ++bj) { f32x4 v0 = acc[ai][bj][m][0], v1 = acc[ai][bj][m][1];
;                     if (ROWSCALE) { v0 = v0 * rs[ai][m]; v1 = v1 * rs[ai][m]; }
;                     if (ACT == 2) {
; #pragma unroll
;                         for (int e = 0; e < 4; ++e) { const float a = fmaxf(v0[e], 0.f), b = fmaxf(v1[e], 0.f); v0[e] = a * a; v1[e] = b * b; } }
;                     u32x4 w; w.x = cvt_pk_bf16(v0[0], v0[1]); w.y = cvt_pk_bf16(v0[2], v0[3]); w.z = cvt_pk_bf16(v1[0], v1[1]); w.w = cvt_pk_bf16(v1[2], v1[3]);
;                     if (col0 + bj * CBS < ncols) *(u32x4*)(rowp + bj * CBS) = w; } }
.LBB0_1316:
	v_lshl_add_u32 v148, s8, 8, v1
	v_ashrrev_i32_e32 v149, 31, v148
	v_max_f32_e32 v122, 0, v122
	v_max_f32_e32 v123, 0, v123
	v_max_f32_e32 v124, 0, v124
	v_lshl_or_b32 v146, s36, 8, v153
	v_lshlrev_b64 v[150:151], 13, v[148:149]
	v_mul_f32_e32 v157, v122, v122
	v_max_f32_e32 v122, v127, v127
	v_mul_f32_e32 v127, v123, v123
	v_max_f32_e32 v123, v128, v128
	v_mul_f32_e32 v128, v124, v124
	v_ashrrev_i32_e32 v147, 31, v146
	v_lshl_add_u64 v[150:151], s[52:53], 0, v[150:151]
	v_max_f32_e32 v122, 0, v122
	v_max_f32_e32 v123, 0, v123
	v_max_f32_e32 v124, 0, v129
	v_max_f32_e32 v125, 0, v125
	v_lshl_add_u64 v[150:151], v[146:147], 1, v[150:151]
	v_max_f32_e32 v126, 0, v126
	v_mul_f32_e32 v122, v122, v122
	v_mul_f32_e32 v123, v123, v123
	v_mul_f32_e32 v124, v124, v124
	v_mul_f32_e32 v125, v125, v125
	v_cmp_gt_i32_e32 vcc, 2.0, v146
	v_mul_f32_e32 v126, v126, v126
	v_cvt_pk_bf16_f32 v122, v126, v122
	v_cvt_pk_bf16_f32 v123, v123, v124
	v_cvt_pk_bf16_f32 v124, v157, v127
	v_cvt_pk_bf16_f32 v125, v128, v125
	global_store_dwordx4 v[150:151], v[122:125], off
	s_nop 0
	v_max_f32_e32 v114, 0, v114
	v_mul_f32_e32 v122, v114, v114
	v_max_f32_e32 v118, 0, v118
	v_max_f32_e32 v114, 0, v119
	v_max_f32_e32 v115, 0, v115
	v_max_f32_e32 v116, 0, v116
	v_mul_f32_e32 v118, v118, v118
	v_mul_f32_e32 v114, v114, v114
	v_mul_f32_e32 v119, v115, v115
	v_max_f32_e32 v115, v120, v120
	v_mul_f32_e32 v120, v116, v116
	v_max_f32_e32 v115, 0, v115
	v_max_f32_e32 v116, 0, v121
	v_max_f32_e32 v117, 0, v117
	v_cvt_pk_bf16_f32 v114, v118, v114
	v_or_b32_e32 v118, 32, v146
	v_mul_f32_e32 v115, v115, v115
	v_mul_f32_e32 v116, v116, v116
	v_mul_f32_e32 v117, v117, v117
	v_cmp_gt_i32_e64 s[8:9], 2.0, v118
	v_cvt_pk_bf16_f32 v115, v115, v116
	v_cvt_pk_bf16_f32 v116, v122, v119
	v_cvt_pk_bf16_f32 v117, v120, v117
	global_store_dwordx4 v[150:151], v[114:117], off offset:64
	s_nop 0
	s_nop 0
	v_or_b32_e32 v114, 16, v148
	v_ashrrev_i32_e32 v115, 31, v114
	v_max_f32_e32 v106, 0, v106
	v_max_f32_e32 v107, 0, v107
	v_max_f32_e32 v108, 0, v108
	v_lshlrev_b64 v[114:115], 13, v[114:115]
	v_mul_f32_e32 v116, v106, v106
	v_max_f32_e32 v106, v111, v111
	v_mul_f32_e32 v111, v107, v107
	v_max_f32_e32 v107, v112, v112
	v_mul_f32_e32 v112, v108, v108
	v_lshl_add_u64 v[114:115], s[52:53], 0, v[114:115]
	v_max_f32_e32 v106, 0, v106
	v_max_f32_e32 v107, 0, v107
	v_max_f32_e32 v108, 0, v113
	v_max_f32_e32 v109, 0, v109
	v_lshl_add_u64 v[114:115], v[146:147], 1, v[114:115]
	v_max_f32_e32 v110, 0, v110
	v_mul_f32_e32 v106, v106, v106
	v_mul_f32_e32 v107, v107, v107
	v_mul_f32_e32 v108, v108, v108
	v_mul_f32_e32 v109, v109, v109
	v_mul_f32_e32 v110, v110, v110
	v_cvt_pk_bf16_f32 v106, v110, v106
	v_cvt_pk_bf16_f32 v107, v107, v108
	v_cvt_pk_bf16_f32 v108, v116, v111
	v_cvt_pk_bf16_f32 v109, v112, v109
	global_store_dwordx4 v[114:115], v[106:109], off
	v_max_f32_e32 v98, 0, v98
	v_max_f32_e32 v99, 0, v99
	v_max_f32_e32 v100, 0, v100
	v_mul_f32_e32 v106, v98, v98
	v_max_f32_e32 v98, v103, v103
	v_mul_f32_e32 v103, v99, v99
	v_max_f32_e32 v99, v104, v104
	v_mul_f32_e32 v104, v100, v100
	v_max_f32_e32 v98, 0, v98
	v_max_f32_e32 v99, 0, v99
	v_max_f32_e32 v100, 0, v105
	v_max_f32_e32 v101, 0, v101
	v_max_f32_e32 v102, 0, v102
	v_mul_f32_e32 v98, v98, v98
	v_mul_f32_e32 v99, v99, v99
	v_mul_f32_e32 v100, v100, v100
	v_mul_f32_e32 v101, v101, v101
	v_mul_f32_e32 v102, v102, v102
	v_cvt_pk_bf16_f32 v98, v102, v98
	v_cvt_pk_bf16_f32 v99, v99, v100
	v_cvt_pk_bf16_f32 v100, v106, v103
	v_cvt_pk_bf16_f32 v101, v104, v101
	global_store_dwordx4 v[114:115], v[98:101], off offset:64
	s_nop 0
	s_nop 0
	v_or_b32_e32 v98, 32, v148
	v_ashrrev_i32_e32 v99, 31, v98
	v_max_f32_e32 v90, 0, v90
	v_max_f32_e32 v91, 0, v91
	v_max_f32_e32 v92, 0, v92
	v_lshlrev_b64 v[98:99], 13, v[98:99]
	v_mul_f32_e32 v100, v90, v90
	v_max_f32_e32 v90, v95, v95
	v_mul_f32_e32 v95, v91, v91
	v_max_f32_e32 v91, v96, v96
	v_mul_f32_e32 v96, v92, v92
	v_lshl_add_u64 v[98:99], s[52:53], 0, v[98:99]
	v_max_f32_e32 v90, 0, v90
	v_max_f32_e32 v91, 0, v91
	v_max_f32_e32 v92, 0, v97
	v_max_f32_e32 v93, 0, v93
	v_lshl_add_u64 v[98:99], v[146:147], 1, v[98:99]
	v_max_f32_e32 v94, 0, v94
	v_mul_f32_e32 v90, v90, v90
	v_mul_f32_e32 v91, v91, v91
	v_mul_f32_e32 v92, v92, v92
	v_mul_f32_e32 v93, v93, v93
	v_mul_f32_e32 v94, v94, v94
	v_cvt_pk_bf16_f32 v90, v94, v90
	v_cvt_pk_bf16_f32 v91, v91, v92
	v_cvt_pk_bf16_f32 v92, v100, v95
	v_cvt_pk_bf16_f32 v93, v96, v93
	global_store_dwordx4 v[98:99], v[90:93], off
	v_max_f32_e32 v82, 0, v82
	v_max_f32_e32 v83, 0, v83
	v_max_f32_e32 v84, 0, v84
	v_mul_f32_e32 v90, v82, v82
	v_max_f32_e32 v82, v87, v87
	v_mul_f32_e32 v87, v83, v83
	v_max_f32_e32 v83, v88, v88
	v_mul_f32_e32 v88, v84, v84
	v_max_f32_e32 v82, 0, v82
	v_max_f32_e32 v83, 0, v83
	v_max_f32_e32 v84, 0, v89
	v_max_f32_e32 v85, 0, v85
	v_max_f32_e32 v86, 0, v86
	v_mul_f32_e32 v82, v82, v82
	v_mul_f32_e32 v83, v83, v83
	v_mul_f32_e32 v84, v84, v84
	v_mul_f32_e32 v85, v85, v85
	v_mul_f32_e32 v86, v86, v86
	v_cvt_pk_bf16_f32 v82, v86, v82
	v_cvt_pk_bf16_f32 v83, v83, v84
	v_cvt_pk_bf16_f32 v84, v90, v87
	v_cvt_pk_bf16_f32 v85, v88, v85
	global_store_dwordx4 v[98:99], v[82:85], off offset:64
	s_nop 0
	s_nop 0
	v_or_b32_e32 v82, 48, v148
	v_ashrrev_i32_e32 v83, 31, v82
	v_max_f32_e32 v74, 0, v74
	v_max_f32_e32 v75, 0, v75
	v_max_f32_e32 v76, 0, v76
	v_lshlrev_b64 v[82:83], 13, v[82:83]
	v_mul_f32_e32 v84, v74, v74
	v_max_f32_e32 v74, v79, v79
	v_mul_f32_e32 v79, v75, v75
	v_max_f32_e32 v75, v80, v80
	v_mul_f32_e32 v80, v76, v76
	v_lshl_add_u64 v[82:83], s[52:53], 0, v[82:83]
	v_max_f32_e32 v74, 0, v74
	v_max_f32_e32 v75, 0, v75
	v_max_f32_e32 v76, 0, v81
; __device__ __forceinline__ unsigned cvt_pk_bf16(float lo, float hi) { unsigned r; asm volatile("v_cvt_pk_bf16_f32 %0, %1, %2" : "=v"(r) : "v"(lo), "v"(hi)); return r; }
;     __device__ __forceinline__ void operator()(const f32x4 (&acc)[2][2][4][2], const Unit& u, int wr, int wc, int fr, int fq) const {
;         const int row0 = u.pm * BM + wr * 64 + fr, col0 = u.pn * BM + wc * CWS + 8 * fq;
;         float rs[2][4];
;         if (ROWSCALE) {
; #pragma unroll
;             for (int ai = 0; ai < 2; ++ai)
; #pragma unroll
;                 for (int m = 0; m < 4; ++m) { const f32x4 q = *(const f32x4*)(ssq4 + (size_t)(row0 + ai * HALF + m * 16) * 4); rs[ai][m] = 1.0f / sqrtf(((q[0] + q[1]) + (q[2] + q[3])) * (1.0f / 1024.0f) + eps); }
;         }
; #pragma unroll
;         for (int ai = 0; ai < 2; ++ai)
; #pragma unroll
;             for (int m = 0; m < 4; ++m) { bf16_t* rowp = O + (size_t)(row0 + ai * HALF + m * 16) * ldc + col0;
; #pragma unroll
;                 for (int bj = 0; bj < 2; ++bj) { f32x4 v0 = acc[ai][bj][m][0], v1 = acc[ai][bj][m][1];
;                     if (ROWSCALE) { v0 = v0 * rs[ai][m]; v1 = v1 * rs[ai][m]; }
;                     if (ACT == 2) {
; #pragma unroll
;                         for (int e = 0; e < 4; ++e) { const float a = fmaxf(v0[e], 0.f), b = fmaxf(v1[e], 0.f); v0[e] = a * a; v1[e] = b * b; } }
;                     u32x4 w; w.x = cvt_pk_bf16(v0[0], v0[1]); w.y = cvt_pk_bf16(v0[2], v0[3]); w.z = cvt_pk_bf16(v1[0], v1[1]); w.w = cvt_pk_bf16(v1[2], v1[3]);
;                     if (col0 + bj * CBS < ncols) *(u32x4*)(rowp + bj * CBS) = w; } }
	v_max_f32_e32 v77, 0, v77
	v_lshl_add_u64 v[82:83], v[146:147], 1, v[82:83]
	v_max_f32_e32 v78, 0, v78
	v_mul_f32_e32 v74, v74, v74
	v_mul_f32_e32 v75, v75, v75
	v_mul_f32_e32 v76, v76, v76
	v_mul_f32_e32 v77, v77, v77
	v_mul_f32_e32 v78, v78, v78
	v_cvt_pk_bf16_f32 v74, v78, v74
	v_cvt_pk_bf16_f32 v75, v75, v76
	v_cvt_pk_bf16_f32 v76, v84, v79
	v_cvt_pk_bf16_f32 v77, v80, v77
	global_store_dwordx4 v[82:83], v[74:77], off
	v_max_f32_e32 v66, 0, v66
	v_max_f32_e32 v67, 0, v67
	v_max_f32_e32 v68, 0, v68
	v_mul_f32_e32 v74, v66, v66
	v_max_f32_e32 v66, v71, v71
	v_mul_f32_e32 v71, v67, v67
	v_max_f32_e32 v67, v72, v72
	v_mul_f32_e32 v72, v68, v68
	v_max_f32_e32 v66, 0, v66
	v_max_f32_e32 v67, 0, v67
	v_max_f32_e32 v68, 0, v73
	v_max_f32_e32 v69, 0, v69
	v_max_f32_e32 v70, 0, v70
	v_mul_f32_e32 v66, v66, v66
	v_mul_f32_e32 v67, v67, v67
	v_mul_f32_e32 v68, v68, v68
	v_mul_f32_e32 v69, v69, v69
	v_mul_f32_e32 v70, v70, v70
	v_cvt_pk_bf16_f32 v66, v70, v66
	v_cvt_pk_bf16_f32 v67, v67, v68
	v_cvt_pk_bf16_f32 v68, v74, v71
	v_cvt_pk_bf16_f32 v69, v72, v69
	global_store_dwordx4 v[82:83], v[66:69], off offset:64
	s_nop 1
	v_lshlrev_b64 v[66:67], 13, v[148:149]
	v_max_f32_e32 v58, 0, v58
	v_max_f32_e32 v59, 0, v59
	v_max_f32_e32 v60, 0, v60
	v_lshl_add_u64 v[66:67], s[52:53], 0, v[66:67]
	v_mul_f32_e32 v68, v58, v58
	v_max_f32_e32 v58, v63, v63
	v_mul_f32_e32 v63, v59, v59
	v_max_f32_e32 v59, v64, v64
	v_mul_f32_e32 v64, v60, v60
	v_lshl_add_u64 v[66:67], v[146:147], 1, v[66:67]
	v_max_f32_e32 v58, 0, v58
	v_max_f32_e32 v59, 0, v59
	v_max_f32_e32 v60, 0, v65
	v_max_f32_e32 v61, 0, v61
	v_lshl_add_u64 v[66:67], v[66:67], 0, s[16:17]
	v_max_f32_e32 v62, 0, v62
	v_mul_f32_e32 v58, v58, v58
	v_mul_f32_e32 v59, v59, v59
	v_mul_f32_e32 v60, v60, v60
	v_mul_f32_e32 v61, v61, v61
	v_mul_f32_e32 v62, v62, v62
	v_cvt_pk_bf16_f32 v58, v62, v58
	v_cvt_pk_bf16_f32 v59, v59, v60
	v_cvt_pk_bf16_f32 v60, v68, v63
	v_cvt_pk_bf16_f32 v61, v64, v61
	global_store_dwordx4 v[66:67], v[58:61], off
	v_max_f32_e32 v50, 0, v50
	v_max_f32_e32 v51, 0, v51
	v_max_f32_e32 v52, 0, v52
	v_mul_f32_e32 v58, v50, v50
	v_max_f32_e32 v50, v55, v55
	v_mul_f32_e32 v55, v51, v51
	v_max_f32_e32 v51, v56, v56
	v_mul_f32_e32 v56, v52, v52
	v_max_f32_e32 v50, 0, v50
	v_max_f32_e32 v51, 0, v51
	v_max_f32_e32 v52, 0, v57
	v_max_f32_e32 v53, 0, v53
	v_max_f32_e32 v54, 0, v54
	v_mul_f32_e32 v50, v50, v50
	v_mul_f32_e32 v51, v51, v51
	v_mul_f32_e32 v52, v52, v52
	v_mul_f32_e32 v53, v53, v53
	v_mul_f32_e32 v54, v54, v54
	v_cvt_pk_bf16_f32 v50, v54, v50
	v_cvt_pk_bf16_f32 v51, v51, v52
	v_cvt_pk_bf16_f32 v52, v58, v55
	v_cvt_pk_bf16_f32 v53, v56, v53
	global_store_dwordx4 v[66:67], v[50:53], off offset:64
	s_nop 1
	v_lshlrev_b64 v[50:51], 13, v[148:149]
	v_max_f32_e32 v42, 0, v42
	v_max_f32_e32 v43, 0, v43
	v_max_f32_e32 v44, 0, v44
	v_lshl_add_u64 v[50:51], s[52:53], 0, v[50:51]
	v_mul_f32_e32 v52, v42, v42
	v_max_f32_e32 v42, v47, v47
	v_mul_f32_e32 v47, v43, v43
	v_max_f32_e32 v43, v48, v48
	v_mul_f32_e32 v48, v44, v44
	v_lshl_add_u64 v[50:51], v[146:147], 1, v[50:51]
	v_max_f32_e32 v42, 0, v42
	v_max_f32_e32 v43, 0, v43
	v_max_f32_e32 v44, 0, v49
	v_max_f32_e32 v45, 0, v45
	v_lshl_add_u64 v[50:51], v[50:51], 0, s[18:19]
	v_max_f32_e32 v46, 0, v46
	v_mul_f32_e32 v42, v42, v42
	v_mul_f32_e32 v43, v43, v43
	v_mul_f32_e32 v44, v44, v44
	v_mul_f32_e32 v45, v45, v45
	v_mul_f32_e32 v46, v46, v46
	v_cvt_pk_bf16_f32 v42, v46, v42
	v_cvt_pk_bf16_f32 v43, v43, v44
	v_cvt_pk_bf16_f32 v44, v52, v47
	v_cvt_pk_bf16_f32 v45, v48, v45
	global_store_dwordx4 v[50:51], v[42:45], off
	v_max_f32_e32 v34, 0, v34
	v_max_f32_e32 v35, 0, v35
	v_max_f32_e32 v36, 0, v36
	v_mul_f32_e32 v42, v34, v34
	v_max_f32_e32 v34, v39, v39
	v_mul_f32_e32 v39, v35, v35
	v_max_f32_e32 v35, v40, v40
; __device__ __forceinline__ unsigned cvt_pk_bf16(float lo, float hi) { unsigned r; asm volatile("v_cvt_pk_bf16_f32 %0, %1, %2" : "=v"(r) : "v"(lo), "v"(hi)); return r; }
;     __device__ __forceinline__ void operator()(const f32x4 (&acc)[2][2][4][2], const Unit& u, int wr, int wc, int fr, int fq) const {
;         const int row0 = u.pm * BM + wr * 64 + fr, col0 = u.pn * BM + wc * CWS + 8 * fq;
;         float rs[2][4];
;         if (ROWSCALE) {
; #pragma unroll
;             for (int ai = 0; ai < 2; ++ai)
; #pragma unroll
;                 for (int m = 0; m < 4; ++m) { const f32x4 q = *(const f32x4*)(ssq4 + (size_t)(row0 + ai * HALF + m * 16) * 4); rs[ai][m] = 1.0f / sqrtf(((q[0] + q[1]) + (q[2] + q[3])) * (1.0f / 1024.0f) + eps); }
;         }
; #pragma unroll
;         for (int ai = 0; ai < 2; ++ai)
; #pragma unroll
;             for (int m = 0; m < 4; ++m) { bf16_t* rowp = O + (size_t)(row0 + ai * HALF + m * 16) * ldc + col0;
; #pragma unroll
;                 for (int bj = 0; bj < 2; ++bj) { f32x4 v0 = acc[ai][bj][m][0], v1 = acc[ai][bj][m][1];
;                     if (ROWSCALE) { v0 = v0 * rs[ai][m]; v1 = v1 * rs[ai][m]; }
;                     if (ACT == 2) {
; #pragma unroll
;                         for (int e = 0; e < 4; ++e) { const float a = fmaxf(v0[e], 0.f), b = fmaxf(v1[e], 0.f); v0[e] = a * a; v1[e] = b * b; } }
;                     u32x4 w; w.x = cvt_pk_bf16(v0[0], v0[1]); w.y = cvt_pk_bf16(v0[2], v0[3]); w.z = cvt_pk_bf16(v1[0], v1[1]); w.w = cvt_pk_bf16(v1[2], v1[3]);
;                     if (col0 + bj * CBS < ncols) *(u32x4*)(rowp + bj * CBS) = w; } }
	v_mul_f32_e32 v40, v36, v36
	v_max_f32_e32 v34, 0, v34
	v_max_f32_e32 v35, 0, v35
	v_max_f32_e32 v36, 0, v41
	v_max_f32_e32 v37, 0, v37
	v_max_f32_e32 v38, 0, v38
	v_mul_f32_e32 v34, v34, v34
	v_mul_f32_e32 v35, v35, v35
	v_mul_f32_e32 v36, v36, v36
	v_mul_f32_e32 v37, v37, v37
	v_mul_f32_e32 v38, v38, v38
	v_cvt_pk_bf16_f32 v34, v38, v34
	v_cvt_pk_bf16_f32 v35, v35, v36
	v_cvt_pk_bf16_f32 v36, v42, v39
	v_cvt_pk_bf16_f32 v37, v40, v37
	global_store_dwordx4 v[50:51], v[34:37], off offset:64
	s_nop 1
	v_lshlrev_b64 v[34:35], 13, v[148:149]
	v_max_f32_e32 v26, 0, v26
	v_max_f32_e32 v27, 0, v27
	v_max_f32_e32 v28, 0, v28
	v_lshl_add_u64 v[34:35], s[52:53], 0, v[34:35]
	v_mul_f32_e32 v36, v26, v26
	v_max_f32_e32 v26, v31, v31
	v_mul_f32_e32 v31, v27, v27
	v_max_f32_e32 v27, v32, v32
	v_mul_f32_e32 v32, v28, v28
	v_lshl_add_u64 v[34:35], v[146:147], 1, v[34:35]
	v_max_f32_e32 v26, 0, v26
	v_max_f32_e32 v27, 0, v27
	v_max_f32_e32 v28, 0, v33
	v_max_f32_e32 v29, 0, v29
	v_lshl_add_u64 v[34:35], v[34:35], 0, s[20:21]
	v_max_f32_e32 v30, 0, v30
	v_mul_f32_e32 v26, v26, v26
	v_mul_f32_e32 v27, v27, v27
	v_mul_f32_e32 v28, v28, v28
	v_mul_f32_e32 v29, v29, v29
	v_mul_f32_e32 v30, v30, v30
	v_cvt_pk_bf16_f32 v26, v30, v26
	v_cvt_pk_bf16_f32 v27, v27, v28
	v_cvt_pk_bf16_f32 v28, v36, v31
	v_cvt_pk_bf16_f32 v29, v32, v29
	global_store_dwordx4 v[34:35], v[26:29], off
	v_max_f32_e32 v18, 0, v18
	v_max_f32_e32 v19, 0, v19
	v_max_f32_e32 v20, 0, v20
	v_mul_f32_e32 v26, v18, v18
	v_max_f32_e32 v18, v23, v23
	v_mul_f32_e32 v23, v19, v19
	v_max_f32_e32 v19, v24, v24
	v_mul_f32_e32 v24, v20, v20
	v_max_f32_e32 v18, 0, v18
	v_max_f32_e32 v19, 0, v19
	v_max_f32_e32 v20, 0, v25
	v_max_f32_e32 v21, 0, v21
	v_max_f32_e32 v22, 0, v22
	v_mul_f32_e32 v18, v18, v18
	v_mul_f32_e32 v19, v19, v19
	v_mul_f32_e32 v20, v20, v20
	v_mul_f32_e32 v21, v21, v21
	v_mul_f32_e32 v22, v22, v22
	v_cvt_pk_bf16_f32 v18, v22, v18
	v_cvt_pk_bf16_f32 v19, v19, v20
	v_cvt_pk_bf16_f32 v20, v26, v23
	v_cvt_pk_bf16_f32 v21, v24, v21
	global_store_dwordx4 v[34:35], v[18:21], off offset:64
	s_nop 1
	v_lshlrev_b64 v[18:19], 13, v[148:149]
	v_max_f32_e32 v10, 0, v10
	v_max_f32_e32 v11, 0, v11
	v_max_f32_e32 v12, 0, v12
	v_lshl_add_u64 v[18:19], s[52:53], 0, v[18:19]
	v_mul_f32_e32 v20, v10, v10
	v_max_f32_e32 v10, v15, v15
	v_mul_f32_e32 v15, v11, v11
	v_max_f32_e32 v11, v16, v16
	v_mul_f32_e32 v16, v12, v12
	v_lshl_add_u64 v[18:19], v[146:147], 1, v[18:19]
	v_max_f32_e32 v10, 0, v10
	v_max_f32_e32 v11, 0, v11
	v_max_f32_e32 v12, 0, v17
	v_max_f32_e32 v13, 0, v13
	v_lshl_add_u64 v[18:19], v[18:19], 0, s[22:23]
	v_max_f32_e32 v14, 0, v14
	v_mul_f32_e32 v10, v10, v10
	v_mul_f32_e32 v11, v11, v11
	v_mul_f32_e32 v12, v12, v12
	v_mul_f32_e32 v13, v13, v13
	v_mul_f32_e32 v14, v14, v14
	v_cvt_pk_bf16_f32 v10, v14, v10
	v_cvt_pk_bf16_f32 v11, v11, v12
	v_cvt_pk_bf16_f32 v12, v20, v15
	v_cvt_pk_bf16_f32 v13, v16, v13
	global_store_dwordx4 v[18:19], v[10:13], off
	v_max_f32_e32 v2, 0, v2
	v_max_f32_e32 v3, 0, v3
	v_max_f32_e32 v4, 0, v4
	v_mul_f32_e32 v10, v2, v2
	v_max_f32_e32 v2, v7, v7
	v_mul_f32_e32 v7, v3, v3
	v_max_f32_e32 v3, v8, v8
	v_mul_f32_e32 v8, v4, v4
	v_max_f32_e32 v2, 0, v2
	v_max_f32_e32 v3, 0, v3
	v_max_f32_e32 v4, 0, v9
	v_max_f32_e32 v5, 0, v5
	v_max_f32_e32 v6, 0, v6
	v_mul_f32_e32 v2, v2, v2
	v_mul_f32_e32 v3, v3, v3
	v_mul_f32_e32 v4, v4, v4
	v_mul_f32_e32 v5, v5, v5
	v_mul_f32_e32 v6, v6, v6
	v_cvt_pk_bf16_f32 v2, v6, v2
	v_cvt_pk_bf16_f32 v3, v3, v4
	v_cvt_pk_bf16_f32 v4, v10, v7
	v_cvt_pk_bf16_f32 v5, v8, v5
	global_store_dwordx4 v[18:19], v[2:5], off offset:64
	s_andn2_b64 vcc, exec, s[6:7]
	s_mov_b64 s[6:7], -1
	s_cbranch_vccnz .LBB0_1305
	s_andn2_b64 vcc, exec, s[0:1]
	s_cbranch_vccnz .LBB0_1304
	s_barrier
	s_branch .LBB0_1304
